# attention fast loops: per-tile LDS-DMA addresses strength-reduced to two persistent 32-bit offsets with SGPR-base DMAs, no m0 save/restore; +0 adds dropped; on top of the previous attention trims
# speedup vs baseline: 1.0107x; 1.0036x over previous
; __device__ __forceinline__ void diff_unit(const bf16* proj, bf16* og0, const float* nwv, float lam_full, float one_m_li, int h, int qb, ldsp lds, int tid, int lane, int wave, int mode) {
;     ...
; #pragma unroll
;     for (int i = 0; i < 3; ++i) { const int n = i < nt ? i : nt - 1; dma_tile(kbase, vbase, 64 * DIFF_TILE(n), lds + i * RSTG, wave, lane); }
; #pragma unroll 1
;     for (int i = 0; i < 2; ++i) {
;         asm volatile("s_waitcnt vmcnt(8)" ::: "memory");
;         __builtin_amdgcn_s_barrier();
;         asm volatile("" ::: "memory");
;         { int n = i + 3; n = n < nt ? n : nt - 1; dma_tile(kbase, vbase, 64 * DIFF_TILE(n), lds + ((i + 3) & 3) * RSTG, wave, lane); }
;         ldsp Ks = lds + (i & 3) * RSTG, Vs = Ks + RKV;
; #pragma unroll 1
;         for (int hh = 0; hh < 2; ++hh) flash_half2<4>(Ks + hh * 32 * 256, Vs + hh * 32 * 256, M, qf, o, mc, l, 64 * (td + i) + 32 * hh, qi, qmin, 1 << 30, lane);
;     }
; #pragma unroll 1
;     for (int i = 2; i < nt; ++i) {
;         asm volatile("s_waitcnt vmcnt(8)" ::: "memory");
;         __builtin_amdgcn_s_barrier();
;         asm volatile("" ::: "memory");
;         { int n = i + 3; n = n < nt ? n : nt - 1; dma_tile(kbase, vbase, 64 * (n - 2), lds + ((i + 3) & 3) * RSTG, wave, lane); }
;         ldsp Ks = lds + (i & 3) * RSTG, Vs = Ks + RKV;
;         flash_fast_tile2<4>(Ks, Vs, M, qf, o, mc, l);
.LBB0_433:
	s_mov_b32 s6, 2
	s_add_i32 s7, s9, 2
	s_or_b32 s8, s9, 1
	s_cmp_lt_u32 5, s7
	s_cselect_b32 s1, 5, s8
	v_lshl_add_u32 v223, s1, 6, v183
	v_add_u32_e32 v225, s35, v223
	v_add_u32_e32 v223, s31, v223
	v_lshlrev_b32_e32 v225, 8, v225
	v_lshlrev_b32_e32 v223, 8, v223
	v_lshl_add_u32 v225, v156, 1, v225
	v_lshl_add_u32 v223, v154, 1, v223
	s_branch .LBB0_435

; #define MFMA32(a, b, c) __builtin_amdgcn_mfma_f32_32x32x16_bf16((a), (b), (c), 0, 0, 0)
; __device__ __forceinline__ bf16x8 cat8(s16x4 lo, s16x4 hi) { return (bf16x8){lo[0], lo[1], lo[2], lo[3], hi[0], hi[1], hi[2], hi[3]}; }
; template <int KS>
; __device__ __forceinline__ void flash_fast_tile2(ldsp Ks, ldsp Vs, const FragMap<KS>& M, const bf16x8 (&qf)[KS], f32x16 (&o)[4], float& mc, float& l) {
;     ...
;         float ps0 = 0.f, ps1 = 0.f;
; #pragma unroll
;         for (int r = 0; r < 16; r += 2) { s0[r] = __builtin_amdgcn_exp2f(s0[r] - mc); s0[r + 1] = __builtin_amdgcn_exp2f(s0[r + 1] - mc); ps0 += s0[r]; ps1 += s0[r + 1]; }
;         l += ps0 + ps1;
;         const bf16x8 p0 = pack8<0>(s0), p1 = pack8<1>(s0);
; #pragma unroll
;         for (int b = 0; b < 4; ++b) {
;             o[b] = MFMA32(cat8(vl[2 * b], vh[2 * b]), p0, o[b]);
;             o[b] = MFMA32(cat8(vl[2 * b + 1], vh[2 * b + 1]), p1, o[b]); }
; __device__ __forceinline__ void diff_unit(const bf16* proj, bf16* og0, const float* nwv, float lam_full, float one_m_li, int h, int qb, ldsp lds, int tid, int lane, int wave, int mode) {
;     ...
;         asm volatile("s_waitcnt vmcnt(8)" ::: "memory");
;         __builtin_amdgcn_s_barrier();
;         asm volatile("" ::: "memory");
;         { int n = i + 3; n = n < nt ? n : nt - 1; dma_tile(kbase, vbase, 64 * (n - 2), lds + ((i + 3) & 3) * RSTG, wave, lane); }
;         ldsp Ks = lds + (i & 3) * RSTG, Vs = Ks + RKV;
;         flash_fast_tile2<4>(Ks, Vs, M, qf, o, mc, l);
.LBB0_435:
	s_add_i32 s0, s6, 3
	s_lshl_b32 s0, s0, 15
	s_and_b32 s0, s0, 0x18000
	s_waitcnt vmcnt(8)
	s_barrier
	s_add_i32 s1, s0, 0x4000
	s_add_i32 m0, s34, s0
	s_add_i32 s4, s6, 4
	global_load_lds_dwordx4 v223, s[24:25]
	s_add_i32 m0, s1, s34
	s_nop 0
	global_load_lds_dwordx4 v223, s[26:27]
	s_add_i32 m0, s36, s0
	s_nop 0
	global_load_lds_dwordx4 v225, s[24:25]
	s_add_i32 m0, s1, s36
	s_cmp_lt_u32 s4, s7
	global_load_lds_dwordx4 v225, s[26:27]
	s_cselect_b32 s4, 0x4000, 0
	v_add_u32_e32 v223, s4, v223
	v_add_u32_e32 v225, s4, v225
	s_lshl_b32 s0, s6, 15
	s_and_b32 s0, s0, 0x18000
	s_add_i32 s9, s0, 0
	v_add_u32_e32 v207, s9, v165
	v_add_u32_e32 v209, s9, v169
	v_add_u32_e32 v208, s9, v167
	ds_read_b128 v[98:101], v207
	ds_read_b128 v[102:105], v208
	v_add_u32_e32 v210, s9, v171
	ds_read_b128 v[106:109], v209
	ds_read_b128 v[110:113], v210
	s_mov_b32 s10, 0
	s_mov_b64 s[0:1], -1
	s_branch .LBB0_437
.LBB0_436:
	v_sub_f32_e32 v66, v66, v206
	v_sub_f32_e32 v67, v67, v206
	v_exp_f32_e32 v66, v66
	v_exp_f32_e32 v67, v67
	v_sub_f32_e32 v68, v68, v206
	v_sub_f32_e32 v69, v69, v206
	v_sub_f32_e32 v70, v70, v206
	v_sub_f32_e32 v71, v71, v206
	v_sub_f32_e32 v72, v72, v206
	v_sub_f32_e32 v73, v73, v206
	v_exp_f32_e32 v68, v68
	v_exp_f32_e32 v69, v69
	v_exp_f32_e32 v70, v70
	v_exp_f32_e32 v71, v71
	v_exp_f32_e32 v72, v72
	v_exp_f32_e32 v73, v73
	v_add_f32_e32 v212, v66, v68
	v_add_f32_e32 v213, v67, v69
	v_cvt_pk_bf16_f32 v66, v66, v67
	v_cvt_pk_bf16_f32 v67, v68, v69
	v_cvt_pk_bf16_f32 v68, v70, v71
	v_cvt_pk_bf16_f32 v69, v72, v73
	v_sub_f32_e32 v74, v74, v206
	v_sub_f32_e32 v75, v75, v206
	v_mfma_f32_32x32x16_bf16 v[50:65], v[142:145], v[66:69], v[50:65]
	v_sub_f32_e32 v76, v76, v206
	v_sub_f32_e32 v77, v77, v206
	v_sub_f32_e32 v78, v78, v206
	v_sub_f32_e32 v79, v79, v206
	v_sub_f32_e32 v80, v80, v206
	v_sub_f32_e32 v81, v81, v206
	v_exp_f32_e32 v74, v74
	s_waitcnt lgkmcnt(10)
	v_mfma_f32_32x32x16_bf16 v[34:49], v[134:137], v[66:69], v[34:49]
	v_exp_f32_e32 v75, v75
	v_exp_f32_e32 v76, v76
	v_exp_f32_e32 v77, v77
	v_exp_f32_e32 v78, v78
	v_exp_f32_e32 v79, v79
	v_exp_f32_e32 v80, v80
	v_exp_f32_e32 v81, v81
	s_waitcnt lgkmcnt(6)
	v_mfma_f32_32x32x16_bf16 v[18:33], v[126:129], v[66:69], v[18:33]
	v_add_f32_e64 v212, v70, v212
	v_add_f32_e64 v213, v71, v213
	v_cvt_pk_bf16_f32 v70, v74, v75
	v_add_f32_e64 v212, v72, v212
	v_add_f32_e64 v213, v73, v213
	v_cvt_pk_bf16_f32 v71, v76, v77
	v_cvt_pk_bf16_f32 v72, v78, v79
	v_cvt_pk_bf16_f32 v73, v80, v81
	v_add_f32_e32 v212, v74, v212
	v_add_f32_e32 v213, v75, v213
	s_waitcnt lgkmcnt(2)
	v_mfma_f32_32x32x16_bf16 v[2:17], v[114:117], v[66:69], v[2:17]
	v_add_f32_e64 v212, v76, v212
	v_add_f32_e64 v213, v77, v213
	s_movk_i32 s10, 0x2000
	v_add_f32_e64 v212, v78, v212
	v_add_f32_e64 v213, v79, v213
	s_mov_b64 s[0:1], 0
	v_add_f32_e32 v212, v80, v212
	v_add_f32_e32 v213, v81, v213
	s_andn2_b64 vcc, exec, s[4:5]
	v_add_f32_e32 v211, v212, v213
	v_mfma_f32_32x32x16_bf16 v[50:65], v[138:141], v[70:73], v[50:65]
	v_add_f32_e32 v195, v195, v211
	v_mfma_f32_32x32x16_bf16 v[34:49], v[130:133], v[70:73], v[34:49]
	v_mfma_f32_32x32x16_bf16 v[18:33], v[122:125], v[70:73], v[18:33]
	s_waitcnt lgkmcnt(0)
	v_mfma_f32_32x32x16_bf16 v[2:17], v[118:121], v[70:73], v[2:17]
	s_cbranch_vccz .LBB0_434

; __device__ __forceinline__ void diff_unit(const bf16* proj, bf16* og0, const float* nwv, float lam_full, float one_m_li, int h, int qb, ldsp lds, int tid, int lane, int wave, int mode) {
;     ...
; #pragma unroll
;     for (int i = 0; i < 3; ++i) { const int n = i < nt ? i : nt - 1; dma_tile(kbase, vbase, 64 * DIFF_TILE(n), lds + i * RSTG, wave, lane); }
; #pragma unroll 1
;     for (int i = 0; i < 2; ++i) {
;         asm volatile("s_waitcnt vmcnt(8)" ::: "memory");
;         __builtin_amdgcn_s_barrier();
;         asm volatile("" ::: "memory");
;         { int n = i + 3; n = n < nt ? n : nt - 1; dma_tile(kbase, vbase, 64 * DIFF_TILE(n), lds + ((i + 3) & 3) * RSTG, wave, lane); }
;         ldsp Ks = lds + (i & 3) * RSTG, Vs = Ks + RKV;
; #pragma unroll 1
;         for (int hh = 0; hh < 2; ++hh) flash_half2<4>(Ks + hh * 32 * 256, Vs + hh * 32 * 256, M, qf, o, mc, l, 64 * (td + i) + 32 * hh, qi, qmin, 1 << 30, lane);
;     }
; #pragma unroll 1
;     for (int i = 2; i < nt; ++i) {
;         asm volatile("s_waitcnt vmcnt(8)" ::: "memory");
;         __builtin_amdgcn_s_barrier();
;         asm volatile("" ::: "memory");
;         { int n = i + 3; n = n < nt ? n : nt - 1; dma_tile(kbase, vbase, 64 * (n - 2), lds + ((i + 3) & 3) * RSTG, wave, lane); }
;         ldsp Ks = lds + (i & 3) * RSTG, Vs = Ks + RKV;
;         flash_fast_tile2<4>(Ks, Vs, M, qf, o, mc, l);
.LBB0_456:
	s_andn2_b64 vcc, exec, s[28:29]
	s_cbranch_vccnz .LBB0_465
	s_mov_b32 s6, 2
	s_cmp_lt_i32 5, s59
	s_cselect_b32 s1, 5, s60
	v_lshl_add_u32 v223, s1, 6, v183
	v_add_u32_e32 v225, s35, v223
	v_add_u32_e32 v223, s31, v223
	v_lshlrev_b32_e32 v225, 8, v225
	v_lshlrev_b32_e32 v223, 8, v223
	v_lshl_add_u32 v225, v156, 1, v225
	v_lshl_add_u32 v223, v154, 1, v223
	s_branch .LBB0_459

; #define MFMA32(a, b, c) __builtin_amdgcn_mfma_f32_32x32x16_bf16((a), (b), (c), 0, 0, 0)
; __device__ __forceinline__ bf16x8 cat8(s16x4 lo, s16x4 hi) { return (bf16x8){lo[0], lo[1], lo[2], lo[3], hi[0], hi[1], hi[2], hi[3]}; }
; template <int KS>
; __device__ __forceinline__ void flash_fast_tile2(ldsp Ks, ldsp Vs, const FragMap<KS>& M, const bf16x8 (&qf)[KS], f32x16 (&o)[4], float& mc, float& l) {
;     ...
;         float ps0 = 0.f, ps1 = 0.f;
; #pragma unroll
;         for (int r = 0; r < 16; r += 2) { s0[r] = __builtin_amdgcn_exp2f(s0[r] - mc); s0[r + 1] = __builtin_amdgcn_exp2f(s0[r + 1] - mc); ps0 += s0[r]; ps1 += s0[r + 1]; }
;         l += ps0 + ps1;
;         const bf16x8 p0 = pack8<0>(s0), p1 = pack8<1>(s0);
; #pragma unroll
;         for (int b = 0; b < 4; ++b) {
;             o[b] = MFMA32(cat8(vl[2 * b], vh[2 * b]), p0, o[b]);
;             o[b] = MFMA32(cat8(vl[2 * b + 1], vh[2 * b + 1]), p1, o[b]); }
; __device__ __forceinline__ void diff_unit(const bf16* proj, bf16* og0, const float* nwv, float lam_full, float one_m_li, int h, int qb, ldsp lds, int tid, int lane, int wave, int mode) {
;     ...
;         asm volatile("s_waitcnt vmcnt(8)" ::: "memory");
;         __builtin_amdgcn_s_barrier();
;         asm volatile("" ::: "memory");
;         { int n = i + 3; n = n < nt ? n : nt - 1; dma_tile(kbase, vbase, 64 * (n - 2), lds + ((i + 3) & 3) * RSTG, wave, lane); }
;         ldsp Ks = lds + (i & 3) * RSTG, Vs = Ks + RKV;
;         flash_fast_tile2<4>(Ks, Vs, M, qf, o, mc, l);
.LBB0_459:
	s_add_i32 s0, s6, 3
	s_lshl_b32 s0, s0, 15
	s_and_b32 s0, s0, 0x18000
	s_waitcnt vmcnt(8)
	s_barrier
	s_add_i32 s1, s0, 0x4000
	s_add_i32 m0, s34, s0
	s_add_i32 s4, s6, 4
	global_load_lds_dwordx4 v223, s[24:25]
	s_add_i32 m0, s1, s34
	s_nop 0
	global_load_lds_dwordx4 v223, s[26:27]
	s_add_i32 m0, s36, s0
	s_nop 0
	global_load_lds_dwordx4 v225, s[24:25]
	s_add_i32 m0, s1, s36
	s_cmp_lt_i32 s4, s59
	global_load_lds_dwordx4 v225, s[26:27]
	s_cselect_b32 s4, 0x4000, 0
	v_add_u32_e32 v223, s4, v223
	v_add_u32_e32 v225, s4, v225
	s_lshl_b32 s0, s6, 15
	s_and_b32 s0, s0, 0x18000
	s_add_i32 s7, s0, 0
	v_add_u32_e32 v0, s7, v165
	v_add_u32_e32 v15, s7, v169
	v_add_u32_e32 v14, s7, v167
	ds_read_b128 v[2:5], v0
	ds_read_b128 v[6:9], v14
	v_add_u32_e32 v209, s7, v171
	ds_read_b128 v[10:13], v15
	ds_read_b128 v[112:115], v209
	s_mov_b32 s28, 0
	s_mov_b64 s[0:1], -1
	s_branch .LBB0_461
.LBB0_460:
	v_sub_f32_e32 v80, v80, v207
	v_sub_f32_e32 v81, v81, v207
	v_exp_f32_e32 v80, v80
	v_exp_f32_e32 v81, v81
	v_sub_f32_e32 v82, v82, v207
	v_sub_f32_e32 v83, v83, v207
	v_sub_f32_e32 v84, v84, v207
	v_sub_f32_e32 v85, v85, v207
	v_sub_f32_e32 v86, v86, v207
	v_sub_f32_e32 v87, v87, v207
	v_exp_f32_e32 v82, v82
	v_exp_f32_e32 v83, v83
	v_exp_f32_e32 v84, v84
	v_exp_f32_e32 v85, v85
	v_exp_f32_e32 v86, v86
	v_exp_f32_e32 v87, v87
	v_add_f32_e32 v252, v80, v82
	v_add_f32_e32 v253, v81, v83
	v_cvt_pk_bf16_f32 v80, v80, v81
	v_cvt_pk_bf16_f32 v81, v82, v83
	v_cvt_pk_bf16_f32 v82, v84, v85
	v_cvt_pk_bf16_f32 v83, v86, v87
	v_sub_f32_e32 v88, v88, v207
	v_sub_f32_e32 v89, v89, v207
	v_mfma_f32_32x32x16_bf16 v[64:79], v[144:147], v[80:83], v[64:79]
	v_sub_f32_e32 v90, v90, v207
	v_sub_f32_e32 v91, v91, v207
	v_sub_f32_e32 v92, v92, v207
	v_sub_f32_e32 v93, v93, v207
	v_sub_f32_e32 v94, v94, v207
	v_sub_f32_e32 v95, v95, v207
	v_exp_f32_e32 v88, v88
	s_waitcnt lgkmcnt(10)
	v_mfma_f32_32x32x16_bf16 v[48:63], v[136:139], v[80:83], v[48:63]
	v_exp_f32_e32 v89, v89
	v_exp_f32_e32 v90, v90
	v_exp_f32_e32 v91, v91
	v_exp_f32_e32 v92, v92
	v_exp_f32_e32 v93, v93
	v_exp_f32_e32 v94, v94
	v_exp_f32_e32 v95, v95
	s_waitcnt lgkmcnt(6)
	v_mfma_f32_32x32x16_bf16 v[32:47], v[128:131], v[80:83], v[32:47]
	v_add_f32_e64 v252, v84, v252
	v_add_f32_e64 v253, v85, v253
	v_cvt_pk_bf16_f32 v84, v88, v89
	v_add_f32_e64 v252, v86, v252
	v_add_f32_e64 v253, v87, v253
	v_cvt_pk_bf16_f32 v85, v90, v91
	v_cvt_pk_bf16_f32 v86, v92, v93
	v_cvt_pk_bf16_f32 v87, v94, v95
	v_add_f32_e32 v252, v88, v252
	v_add_f32_e32 v253, v89, v253
	s_waitcnt lgkmcnt(2)
	v_mfma_f32_32x32x16_bf16 v[16:31], v[116:119], v[80:83], v[16:31]
	v_add_f32_e64 v252, v90, v252
	v_add_f32_e64 v253, v91, v253
	s_movk_i32 s28, 0x2000
	v_add_f32_e64 v252, v92, v252
	v_add_f32_e64 v253, v93, v253
	s_mov_b64 s[0:1], 0
	v_add_f32_e32 v252, v94, v252
	v_add_f32_e32 v253, v95, v253
	s_andn2_b64 vcc, exec, s[4:5]
	v_add_f32_e32 v211, v252, v253
	v_mfma_f32_32x32x16_bf16 v[64:79], v[140:143], v[84:87], v[64:79]
	v_add_f32_e32 v195, v195, v211
	v_mfma_f32_32x32x16_bf16 v[48:63], v[132:135], v[84:87], v[48:63]
	v_mfma_f32_32x32x16_bf16 v[32:47], v[124:127], v[84:87], v[32:47]
	s_waitcnt lgkmcnt(0)
	v_mfma_f32_32x32x16_bf16 v[16:31], v[120:123], v[84:87], v[16:31]
	s_cbranch_vccz .LBB0_458
